# sample_dn: the four gate loads of the j<8 block issued with the first set-up section's loads
# baseline (speedup 1.0000x reference)
.LBB0_608:
	v_mov_b32_e32 v13, v176
	v_mov_b32_e32 v29, v17
	v_ashrrev_i32_e32 v0, 7, v13
	v_lshl_add_u32 v30, s44, 2, v0
	v_mul_lo_u32 v0, v0, s82
	v_and_b32_e32 v4, -8, v30
	v_and_b32_e32 v9, 7, v30
	v_add_u32_e32 v156, 0, v0
	v_add_u32_e32 v26, 0x2000, v4
	v_mov_b64_e32 v[0:1], s[30:31]
	v_and_b32_e32 v72, 0x7f, v13
	v_mad_i64_i32 v[2:3], s[4:5], v26, s37, v[0:1]
	v_lshlrev_b32_e32 v16, 8, v9
	v_lshl_add_u64 v[2:3], v[2:3], 0, v[16:17]
	v_lshlrev_b32_e32 v28, 1, v72
	v_lshl_add_u64 v[2:3], v[2:3], 0, v[28:29]
	v_add_co_u32_e32 v2, vcc, s47, v2
	v_add_u32_e32 v24, 0x2001, v4
	v_addc_co_u32_e32 v3, vcc, 0, v3, vcc
	global_load_ushort v240, v[2:3], off offset:2048
	v_lshl_add_u32 v155, v72, 2, v156
	v_add_u32_e32 v20, 0x2002, v4
	v_add_u32_e32 v14, 0x2003, v4
	v_add_u32_e32 v22, 0x2004, v4
	v_add_u32_e32 v12, 0x2005, v4
	v_add_u32_e32 v10, 0x2006, v4
	v_add_u32_e32 v8, 0x2007, v4
	v_lshlrev_b32_e32 v157, 7, v9
	v_or_b32_e32 v15, v157, v72
	v_bfe_u32 v11, v13, 6, 1
	v_and_b32_e32 v13, 63, v13
	v_lshl_add_u32 v162, v11, 6, v156
	v_mad_i64_i32 v[2:3], s[4:5], v24, s37, v[0:1]
	v_lshl_add_u64 v[2:3], v[2:3], 0, v[16:17]
	v_lshl_add_u64 v[2:3], v[2:3], 0, v[28:29]
	v_add_co_u32_e32 v2, vcc, s47, v2
	s_nop 1
	v_addc_co_u32_e32 v3, vcc, 0, v3, vcc
	global_load_ushort v241, v[2:3], off offset:2048
	v_mad_i64_i32 v[2:3], s[4:5], v20, s37, v[0:1]
	v_lshl_add_u64 v[2:3], v[2:3], 0, v[16:17]
	v_lshl_add_u64 v[2:3], v[2:3], 0, v[28:29]
	v_add_co_u32_e32 v2, vcc, s47, v2
	s_nop 1
	v_addc_co_u32_e32 v3, vcc, 0, v3, vcc
	global_load_ushort v243, v[2:3], off offset:2048
	v_mad_i64_i32 v[2:3], s[4:5], v14, s37, v[0:1]
	v_lshl_add_u64 v[2:3], v[2:3], 0, v[16:17]
	v_lshl_add_u64 v[2:3], v[2:3], 0, v[28:29]
	v_add_co_u32_e32 v2, vcc, s47, v2
	s_nop 1
	v_addc_co_u32_e32 v3, vcc, 0, v3, vcc
	global_load_ushort v244, v[2:3], off offset:2048
	v_mad_i64_i32 v[2:3], s[4:5], v22, s37, v[0:1]
	v_lshl_add_u64 v[2:3], v[2:3], 0, v[16:17]
	v_lshl_add_u64 v[2:3], v[2:3], 0, v[28:29]
	v_add_co_u32_e32 v2, vcc, s47, v2
	s_nop 1
	v_addc_co_u32_e32 v3, vcc, 0, v3, vcc
	global_load_ushort v246, v[2:3], off offset:2048
	v_mad_i64_i32 v[2:3], s[4:5], v12, s37, v[0:1]
	v_lshl_add_u64 v[2:3], v[2:3], 0, v[16:17]
	v_lshl_add_u64 v[2:3], v[2:3], 0, v[28:29]
	v_add_co_u32_e32 v2, vcc, s47, v2
	s_nop 1
	v_addc_co_u32_e32 v3, vcc, 0, v3, vcc
	global_load_ushort v247, v[2:3], off offset:2048
	v_mad_i64_i32 v[2:3], s[4:5], v10, s37, v[0:1]
	v_lshl_add_u64 v[2:3], v[2:3], 0, v[16:17]
	v_lshl_add_u64 v[2:3], v[2:3], 0, v[28:29]
	v_mad_i64_i32 v[0:1], s[4:5], v8, s37, v[0:1]
	v_add_co_u32_e32 v2, vcc, s47, v2
	v_lshl_add_u64 v[0:1], v[0:1], 0, v[16:17]
	v_addc_co_u32_e32 v3, vcc, 0, v3, vcc
	v_lshl_add_u64 v[0:1], v[0:1], 0, v[28:29]
	v_add_co_u32_e32 v0, vcc, s47, v0
	global_load_ushort v249, v[2:3], off offset:2048
	v_addc_co_u32_e32 v1, vcc, 0, v1, vcc
	global_load_ushort v250, v[0:1], off offset:2048
	v_lshlrev_b32_e32 v16, 2, v15
	global_load_dword v56, v16, s[84:85]
	v_cmp_gt_u32_e64 s[6:7], 8, v72
	s_and_saveexec_b64 s[8:9], s[6:7]
	v_or_b32_e32 v100, v26, v72
	v_ashrrev_i32_e32 v101, 31, v100
	v_lshlrev_b64 v[100:101], 7, v[100:101]
	v_lshlrev_b32_e32 v102, 2, v9
	v_mov_b32_e32 v103, v17
	v_lshl_add_u64 v[100:101], s[80:81], 0, v[100:101]
	v_lshl_add_u64 v[100:101], v[100:101], 0, v[102:103]
	global_load_dword v104, v[100:101], off offset:32
	global_load_dword v105, v102, s[88:89]
	global_load_dword v106, v102, s[86:87]
	global_load_dword v107, v[100:101], off
	s_mov_b64 exec, s[8:9]
	s_waitcnt vmcnt(0)
	v_lshlrev_b32_e32 v5, 16, v240
	v_lshlrev_b32_e32 v242, 16, v241
	ds_write2st64_b32 v155, v5, v242 offset0:64 offset1:66
	v_lshlrev_b32_e32 v5, 16, v243
	v_lshlrev_b32_e32 v245, 16, v244
	ds_write2st64_b32 v155, v5, v245 offset0:68 offset1:70
	v_lshlrev_b32_e32 v5, 16, v246
	v_lshlrev_b32_e32 v248, 16, v247
	ds_write2st64_b32 v155, v5, v248 offset0:72 offset1:74
	v_lshlrev_b32_e32 v2, 16, v249
	v_lshlrev_b32_e32 v0, 16, v250
	ds_write2st64_b32 v155, v2, v0 offset0:76 offset1:78
	v_ashrrev_i32_e32 v0, 3, v30
	v_lshl_add_u32 v23, v0, 1, v0
	v_lshl_add_u64 v[0:1], s[68:69], 0, v[16:17]
	v_mad_i64_i32 v[2:3], s[4:5], v23, s39, v[0:1]
	v_add_u32_e32 v19, 1, v23
	v_add_u32_e32 v21, 2, v23
	global_load_dword v58, v[2:3], off
	v_mad_i64_i32 v[2:3], s[4:5], v19, s39, v[0:1]
	v_mad_i64_i32 v[0:1], s[4:5], v21, s39, v[0:1]
	global_load_dword v46, v[2:3], off
	global_load_dword v59, v[0:1], off
	v_lshlrev_b32_e32 v0, 1, v15
	v_mov_b32_e32 v1, v17
	v_lshl_add_u64 v[4:5], s[30:31], 0, v[0:1]
	v_mad_i64_i32 v[6:7], s[4:5], v26, s37, v[4:5]
	global_load_ushort v0, v[6:7], off
	v_mad_i64_i32 v[36:37], s[4:5], v24, s37, v[4:5]
	v_mad_i64_i32 v[38:39], s[4:5], v20, s37, v[4:5]
	v_mad_i64_i32 v[48:49], s[4:5], v14, s37, v[4:5]
	v_mad_i64_i32 v[60:61], s[4:5], v22, s37, v[4:5]
	v_mad_i64_i32 v[62:63], s[4:5], v12, s37, v[4:5]
	v_mad_i64_i32 v[64:65], s[4:5], v10, s37, v[4:5]
	v_mad_i64_i32 v[66:67], s[4:5], v8, s37, v[4:5]
	v_lshl_add_u64 v[4:5], s[84:85], 0, v[16:17]
	v_add_co_u32_e32 v32, vcc, s39, v4
	v_or_b32_e32 v16, 0x1000, v16
	s_nop 0
	v_addc_co_u32_e32 v33, vcc, 0, v5, vcc
	global_load_dword v57, v[32:33], off
	v_add_co_u32_e32 v32, vcc, s82, v4
	v_or_b32_e32 v15, 0x800, v15
	s_nop 0
	v_addc_co_u32_e32 v33, vcc, 0, v5, vcc
	v_add_co_u32_e32 v4, vcc, s97, v4
	global_load_dword v32, v[32:33], off
	s_nop 0
	v_addc_co_u32_e32 v5, vcc, 0, v5, vcc
	global_load_dword v34, v[4:5], off
	v_lshl_add_u64 v[4:5], s[68:69], 0, v[16:17]
	v_mad_i64_i32 v[40:41], s[4:5], v23, s39, v[4:5]
	global_load_dword v50, v[40:41], off
	v_mad_i64_i32 v[40:41], s[4:5], v19, s39, v[4:5]
	v_mad_i64_i32 v[4:5], s[4:5], v21, s39, v[4:5]
	global_load_dword v54, v[40:41], off
	global_load_ushort v1, v[62:63], off
	global_load_ushort v3, v[66:67], off
	global_load_ushort v2, v[64:65], off
	s_waitcnt vmcnt(8)
	v_lshlrev_b32_e32 v52, 16, v0
	global_load_ushort v0, v[36:37], off
	s_waitcnt vmcnt(8)
	v_pk_mul_f32 v[68:69], v[58:59], v[56:57]
	s_waitcnt vmcnt(3)
	v_lshlrev_b32_e32 v1, 16, v1
	s_waitcnt vmcnt(2)
	v_lshlrev_b32_e32 v3, 16, v3
	s_waitcnt vmcnt(1)
	v_lshlrev_b32_e32 v2, 16, v2
	s_waitcnt vmcnt(0)
	v_lshlrev_b32_e32 v53, 16, v0
	global_load_ushort v0, v[38:39], off
	s_waitcnt vmcnt(0)
	v_lshlrev_b32_e32 v42, 16, v0
	global_load_ushort v0, v[48:49], off
	s_waitcnt vmcnt(0)
	v_lshlrev_b32_e32 v43, 16, v0
	global_load_ushort v0, v[60:61], off
	global_load_dword v51, v[4:5], off
	s_nop 0
	global_load_ushort v4, v[6:7], off offset:2048
	global_load_ushort v5, v[62:63], off offset:2048
	s_waitcnt vmcnt(3)
	v_lshlrev_b32_e32 v0, 16, v0
	s_waitcnt vmcnt(1)
	v_lshlrev_b32_e32 v44, 16, v4
	global_load_ushort v4, v[36:37], off offset:2048
	global_load_ushort v6, v[64:65], off offset:2048
	s_waitcnt vmcnt(2)
	v_lshlrev_b32_e32 v5, 16, v5
	global_load_ushort v7, v[66:67], off offset:2048
	v_pk_mov_b32 v[66:67], v[58:59], v[52:53] op_sel:[1,0]
	v_mov_b32_e32 v58, v59
	v_mov_b32_e32 v59, v53
	s_waitcnt vmcnt(2)
	v_lshlrev_b32_e32 v45, 16, v4
	global_load_ushort v4, v[38:39], off offset:2048
	v_lshl_add_u64 v[38:39], s[84:85], 0, v[16:17]
	v_add_co_u32_e32 v36, vcc, s39, v38
	v_pk_mov_b32 v[70:71], v[50:51], v[44:45] op_sel:[1,0]
	s_nop 0
	v_addc_co_u32_e32 v37, vcc, 0, v39, vcc
	s_waitcnt vmcnt(2)
	v_lshlrev_b32_e32 v6, 16, v6
	s_waitcnt vmcnt(1)
	v_lshlrev_b32_e32 v7, 16, v7
	s_waitcnt vmcnt(0)
	v_lshlrev_b32_e32 v40, 16, v4
	global_load_ushort v4, v[48:49], off offset:2048
	s_waitcnt vmcnt(0)
	v_lshlrev_b32_e32 v41, 16, v4
	global_load_dword v48, v16, s[84:85]
	global_load_dword v49, v[36:37], off
	v_lshlrev_b32_e32 v16, 2, v15
	global_load_ushort v4, v[60:61], off offset:2048
	v_lshl_add_u64 v[60:61], s[68:69], 0, v[16:17]
	v_mad_i64_i32 v[62:63], s[4:5], v19, s39, v[60:61]
	global_load_dword v25, v[62:63], off
	v_mad_i64_i32 v[62:63], s[4:5], v21, s39, v[60:61]
	v_mad_i64_i32 v[60:61], s[4:5], v23, s39, v[60:61]
	global_load_dword v27, v[62:63], off
	global_load_dword v23, v[60:61], off
	v_lshlrev_b32_e32 v62, 1, v15
	v_mov_b32_e32 v63, v17
	v_lshl_add_u64 v[62:63], s[30:31], 0, v[62:63]
	v_mad_i64_i32 v[64:65], s[4:5], v26, s37, v[62:63]
	global_load_ushort v15, v[64:65], off
	v_mad_i64_i32 v[64:65], s[4:5], v24, s37, v[62:63]
	v_add_co_u32_e32 v36, vcc, s82, v38
	s_waitcnt vmcnt(5)
	v_pk_mul_f32 v[74:75], v[50:51], v[48:49]
	v_addc_co_u32_e32 v37, vcc, 0, v39, vcc
	v_add_co_u32_e32 v38, vcc, s97, v38
	global_load_dword v36, v[36:37], off
	s_nop 0
	v_addc_co_u32_e32 v39, vcc, 0, v39, vcc
	global_load_dword v38, v[38:39], off
	v_mov_b32_e32 v50, v51
	v_mov_b32_e32 v51, v45
	s_waitcnt vmcnt(6)
	v_lshlrev_b32_e32 v4, 16, v4
	s_waitcnt vmcnt(2)
	v_lshlrev_b32_e32 v29, 16, v15
	global_load_ushort v15, v[64:65], off
	v_mad_i64_i32 v[64:65], s[4:5], v20, s37, v[62:63]
	s_waitcnt vmcnt(0)
	v_lshlrev_b32_e32 v31, 16, v15
	global_load_ushort v15, v[64:65], off
	v_mad_i64_i32 v[64:65], s[4:5], v14, s37, v[62:63]
	s_waitcnt vmcnt(0)
	v_lshlrev_b32_e32 v33, 16, v15
	global_load_ushort v15, v[64:65], off
	v_mad_i64_i32 v[64:65], s[4:5], v22, s37, v[62:63]
	s_waitcnt vmcnt(0)
	v_lshlrev_b32_e32 v21, 16, v15
	global_load_ushort v15, v[64:65], off
	v_mad_i64_i32 v[64:65], s[4:5], v12, s37, v[62:63]
	global_load_ushort v19, v[64:65], off
	v_mad_i64_i32 v[64:65], s[4:5], v10, s37, v[62:63]
	v_mad_i64_i32 v[62:63], s[4:5], v8, s37, v[62:63]
	global_load_ushort v35, v[64:65], off
	global_load_ushort v37, v[62:63], off
	v_lshl_add_u64 v[62:63], s[84:85], 0, v[16:17]
	v_add_co_u32_e32 v64, vcc, s39, v62
	global_load_dword v16, v16, s[84:85]
	s_nop 0
	v_addc_co_u32_e32 v65, vcc, 0, v63, vcc
	global_load_dword v39, v[64:65], off
	v_add_co_u32_e32 v64, vcc, s82, v62
	v_cmp_eq_u32_e64 s[4:5], 0, v13
	s_nop 0
	v_addc_co_u32_e32 v65, vcc, 0, v63, vcc
	v_add_co_u32_e32 v62, vcc, s97, v62
	global_load_dword v47, v[64:65], off
	s_nop 0
	v_addc_co_u32_e32 v63, vcc, 0, v63, vcc
	global_load_dword v55, v[62:63], off
	v_mov_b32_e32 v62, v57
	v_mov_b32_e32 v63, v56
	v_pk_mov_b32 v[64:65], v[44:45], v[40:41] op_sel:[1,0]
	s_waitcnt vmcnt(7)
	v_lshlrev_b32_e32 v15, 16, v15
	s_waitcnt vmcnt(6)
	v_lshlrev_b32_e32 v19, 16, v19
	s_waitcnt vmcnt(5)
	v_lshlrev_b32_e32 v35, 16, v35
	s_waitcnt vmcnt(4)
	v_lshlrev_b32_e32 v37, 16, v37
	s_waitcnt vmcnt(3)
	v_mul_f32_e32 v23, v16, v23
	s_waitcnt vmcnt(2)
	v_fmac_f32_e32 v23, v25, v39
	s_waitcnt vmcnt(1)
	v_fmac_f32_e32 v23, v27, v47
	s_waitcnt vmcnt(0)
	v_fmac_f32_e32 v23, v55, v29
	v_mul_f32_e32 v60, 0xbfb8aa3b, v23
	v_exp_f32_e32 v60, v60
	s_nop 0
	v_add_f32_e32 v60, 1.0, v60
	v_rcp_f32_e32 v60, v60
	s_nop 0
	v_mul_f32_e32 v23, v23, v60
	v_mul_f32_e32 v60, v27, v39
	v_fmac_f32_e32 v60, v25, v16
	v_fmac_f32_e32 v60, v47, v29
	v_fmac_f32_e32 v60, v55, v31
	v_mul_f32_e32 v25, 0xbfb8aa3b, v60
	v_exp_f32_e32 v25, v25
	s_nop 0
	v_add_f32_e32 v25, 1.0, v25
	v_rcp_f32_e32 v25, v25
	s_nop 0
	v_mul_f32_e32 v25, v60, v25
	ds_write2st64_b32 v155, v23, v25 offset0:32 offset1:34
	v_mul_f32_e32 v23, v39, v29
	v_fmac_f32_e32 v23, v27, v16
	v_fmac_f32_e32 v23, v47, v31
	v_fmac_f32_e32 v23, v55, v33
	v_mul_f32_e32 v25, 0xbfb8aa3b, v23
	v_exp_f32_e32 v25, v25
	v_pk_mov_b32 v[60:61], v[52:53], v[42:43] op_sel:[1,0]
	v_add_f32_e32 v25, 1.0, v25
	v_rcp_f32_e32 v25, v25
	s_nop 0
	v_mul_f32_e32 v23, v23, v25
	v_mul_f32_e32 v25, v39, v31
	v_fmac_f32_e32 v25, v16, v29
	v_fmac_f32_e32 v25, v47, v33
	v_fmac_f32_e32 v25, v55, v21
	v_mul_f32_e32 v27, 0xbfb8aa3b, v25
	v_exp_f32_e32 v27, v27
	s_nop 0
	v_add_f32_e32 v27, 1.0, v27
	v_rcp_f32_e32 v27, v27
	s_nop 0
	v_mul_f32_e32 v25, v25, v27
	ds_write2st64_b32 v155, v23, v25 offset0:36 offset1:38
	v_mul_f32_e32 v23, v39, v33
	v_fmac_f32_e32 v23, v16, v31
	v_fmac_f32_e32 v23, v47, v21
	v_fmac_f32_e32 v23, v55, v15
	v_mul_f32_e32 v25, 0xbfb8aa3b, v23
	v_exp_f32_e32 v25, v25
	s_nop 0
	v_add_f32_e32 v25, 1.0, v25
	v_rcp_f32_e32 v25, v25
	s_nop 0
	v_mul_f32_e32 v23, v23, v25
	v_mul_f32_e32 v25, v39, v21
	v_fmac_f32_e32 v25, v16, v33
	v_fmac_f32_e32 v25, v47, v15
	v_fmac_f32_e32 v25, v55, v19
	v_mul_f32_e32 v27, 0xbfb8aa3b, v25
	v_exp_f32_e32 v27, v27
	s_nop 0
	v_add_f32_e32 v27, 1.0, v27
	v_rcp_f32_e32 v27, v27
	s_nop 0
	v_mul_f32_e32 v25, v25, v27
	ds_write2st64_b32 v155, v23, v25 offset0:40 offset1:42
	v_mul_f32_e32 v23, v39, v15
	v_fmac_f32_e32 v23, v16, v21
	v_fmac_f32_e32 v23, v47, v19
	v_mul_f32_e32 v19, v39, v19
	v_fmac_f32_e32 v19, v16, v15
	v_fmac_f32_e32 v19, v47, v35
	v_fmac_f32_e32 v23, v55, v35
	v_fmac_f32_e32 v19, v55, v37
	v_mul_f32_e32 v21, 0xbfb8aa3b, v23
	v_mul_f32_e32 v15, 0xbfb8aa3b, v19
	v_exp_f32_e32 v21, v21
	v_exp_f32_e32 v15, v15
	v_xor_b32_e32 v16, 32, v187
	v_pk_fma_f32 v[46:47], v[46:47], v[62:63], v[68:69] op_sel_hi:[0,1,1]
	v_add_f32_e32 v21, 1.0, v21
	v_add_f32_e32 v15, 1.0, v15
	v_rcp_f32_e32 v21, v21
	v_rcp_f32_e32 v15, v15
	v_pk_fma_f32 v[46:47], v[32:33], v[66:67], v[46:47] op_sel_hi:[0,1,1]
	v_pk_fma_f32 v[46:47], v[34:35], v[52:53], v[46:47] op_sel_hi:[0,1,1]
	v_mul_f32_e32 v21, v23, v21
	v_mul_f32_e32 v15, v19, v15
	ds_write2st64_b32 v155, v21, v15 offset0:44 offset1:46
	v_and_b32_e32 v15, 64, v187
	v_add_u32_e32 v15, 64, v15
	v_cmp_lt_i32_e32 vcc, v16, v15
	s_nop 1
	v_cndmask_b32_e32 v16, v187, v16, vcc
	v_lshlrev_b32_e32 v161, 2, v16
	v_xor_b32_e32 v16, 16, v187
	v_cmp_lt_i32_e32 vcc, v16, v15
	s_nop 1
	v_cndmask_b32_e32 v16, v187, v16, vcc
	v_lshlrev_b32_e32 v160, 2, v16
	v_xor_b32_e32 v16, 8, v187
	v_cmp_lt_i32_e32 vcc, v16, v15
	s_nop 1
	v_cndmask_b32_e32 v16, v187, v16, vcc
	v_lshlrev_b32_e32 v159, 2, v16
	v_xor_b32_e32 v16, 4, v187
	v_cmp_lt_i32_e32 vcc, v16, v15
	s_nop 1
	v_cndmask_b32_e32 v16, v187, v16, vcc
	v_lshlrev_b32_e32 v158, 2, v16
	v_xor_b32_e32 v16, 2, v187
	v_cmp_lt_i32_e32 vcc, v16, v15
	s_nop 1
	v_cndmask_b32_e32 v16, v187, v16, vcc
	v_lshlrev_b32_e32 v29, 2, v16
	v_mul_f32_e32 v16, 0xbfb8aa3b, v46
	v_exp_f32_e32 v16, v16
	s_nop 0
	v_add_f32_e32 v16, 1.0, v16
	v_rcp_f32_e32 v66, v16
	v_mul_f32_e32 v16, 0xbfb8aa3b, v47
	v_exp_f32_e32 v16, v16
	s_nop 0
	v_add_f32_e32 v16, 1.0, v16
	v_rcp_f32_e32 v67, v16
	s_nop 0
	v_pk_mul_f32 v[46:47], v[46:47], v[66:67]
	v_pk_mul_f32 v[66:67], v[56:57], v[58:59]
	v_pk_mul_f32 v[58:59], v[46:47], v[46:47]
	ds_bpermute_b32 v58, v161, v58
	ds_bpermute_b32 v59, v161, v59
	s_waitcnt lgkmcnt(0)
	v_pk_fma_f32 v[58:59], v[46:47], v[46:47], v[58:59]
	ds_bpermute_b32 v68, v160, v58
	ds_bpermute_b32 v69, v160, v59
	s_waitcnt lgkmcnt(0)
	v_pk_add_f32 v[58:59], v[58:59], v[68:69]
	ds_bpermute_b32 v68, v159, v58
	ds_bpermute_b32 v69, v159, v59
	s_waitcnt lgkmcnt(0)
	v_pk_add_f32 v[58:59], v[58:59], v[68:69]
	ds_bpermute_b32 v68, v158, v58
	ds_bpermute_b32 v69, v158, v59
	s_waitcnt lgkmcnt(0)
	v_pk_add_f32 v[58:59], v[58:59], v[68:69]
	ds_bpermute_b32 v68, v29, v58
	ds_bpermute_b32 v69, v29, v59
	s_waitcnt lgkmcnt(0)
	v_pk_add_f32 v[58:59], v[58:59], v[68:69]
	v_mov_b32_e32 v68, v53
	v_pk_fma_f32 v[52:53], v[62:63], v[52:53], v[66:67] op_sel_hi:[1,0,1]
	v_mov_b32_e32 v69, v43
	v_pk_fma_f32 v[52:53], v[32:33], v[60:61], v[52:53] op_sel_hi:[0,1,1]
	v_pk_fma_f32 v[52:53], v[34:35], v[42:43], v[52:53] op_sel_hi:[0,1,1]
	v_mul_f32_e32 v16, 0xbfb8aa3b, v52
	v_exp_f32_e32 v16, v16
	v_pk_mul_f32 v[68:69], v[56:57], v[68:69]
	v_add_f32_e32 v16, 1.0, v16
	v_rcp_f32_e32 v60, v16
	v_mul_f32_e32 v16, 0xbfb8aa3b, v53
	v_exp_f32_e32 v16, v16
	s_nop 0
	v_add_f32_e32 v16, 1.0, v16
	v_rcp_f32_e32 v61, v16
	s_nop 0
	v_pk_mul_f32 v[52:53], v[52:53], v[60:61]
	s_nop 0
	v_pk_mul_f32 v[60:61], v[52:53], v[52:53]
	ds_bpermute_b32 v60, v161, v60
	ds_bpermute_b32 v61, v161, v61
	s_waitcnt lgkmcnt(0)
	v_pk_fma_f32 v[60:61], v[52:53], v[52:53], v[60:61]
	ds_bpermute_b32 v66, v160, v60
	ds_bpermute_b32 v67, v160, v61
	s_waitcnt lgkmcnt(0)
	v_pk_add_f32 v[60:61], v[60:61], v[66:67]
	ds_bpermute_b32 v66, v159, v60
	ds_bpermute_b32 v67, v159, v61
	s_waitcnt lgkmcnt(0)
	v_pk_add_f32 v[60:61], v[60:61], v[66:67]
	ds_bpermute_b32 v66, v158, v60
	ds_bpermute_b32 v67, v158, v61
	s_waitcnt lgkmcnt(0)
	v_pk_add_f32 v[60:61], v[60:61], v[66:67]
	ds_bpermute_b32 v66, v29, v60
	ds_bpermute_b32 v67, v29, v61
	s_waitcnt lgkmcnt(0)
	v_pk_add_f32 v[60:61], v[60:61], v[66:67]
	v_mov_b32_e32 v66, v43
	v_mov_b32_e32 v67, v1
	v_pk_mul_f32 v[66:67], v[56:57], v[66:67]
	v_pk_mov_b32 v[56:57], v[42:43], v[0:1] op_sel:[1,0]
	v_pk_fma_f32 v[42:43], v[62:63], v[42:43], v[68:69] op_sel_hi:[1,0,1]
	s_nop 0
	v_pk_fma_f32 v[42:43], v[32:33], v[56:57], v[42:43] op_sel_hi:[0,1,1]
	v_pk_fma_f32 v[42:43], v[34:35], v[0:1], v[42:43] op_sel_hi:[0,1,1]
	v_mul_f32_e32 v16, 0xbfb8aa3b, v43
	v_exp_f32_e32 v16, v16
	s_nop 0
	v_add_f32_e32 v16, 1.0, v16
	v_rcp_f32_e32 v57, v16
	v_mul_f32_e32 v16, 0xbfb8aa3b, v42
	v_exp_f32_e32 v16, v16
	s_nop 0
	v_add_f32_e32 v16, 1.0, v16
	v_rcp_f32_e32 v56, v16
	s_nop 0
	v_pk_mul_f32 v[42:43], v[42:43], v[56:57]
	s_nop 0
	v_pk_mul_f32 v[56:57], v[42:43], v[42:43]
	ds_bpermute_b32 v57, v161, v57
	ds_bpermute_b32 v56, v161, v56
	s_waitcnt lgkmcnt(0)
	v_pk_fma_f32 v[56:57], v[42:43], v[42:43], v[56:57]
	ds_bpermute_b32 v69, v160, v57
	ds_bpermute_b32 v68, v160, v56
	s_waitcnt lgkmcnt(0)
	v_pk_add_f32 v[56:57], v[56:57], v[68:69]
	ds_bpermute_b32 v69, v159, v57
	ds_bpermute_b32 v68, v159, v56
	s_waitcnt lgkmcnt(0)
	v_pk_add_f32 v[56:57], v[56:57], v[68:69]
	ds_bpermute_b32 v69, v158, v57
	ds_bpermute_b32 v68, v158, v56
	s_waitcnt lgkmcnt(0)
	v_pk_add_f32 v[56:57], v[56:57], v[68:69]
	ds_bpermute_b32 v68, v29, v56
	ds_bpermute_b32 v69, v29, v57
	s_waitcnt lgkmcnt(0)
	v_pk_add_f32 v[56:57], v[56:57], v[68:69]
	v_mov_b32_e32 v68, v49
	v_mov_b32_e32 v69, v48
	v_pk_fma_f32 v[54:55], v[54:55], v[68:69], v[74:75] op_sel_hi:[0,1,1]
	v_pk_fma_f32 v[54:55], v[36:37], v[70:71], v[54:55] op_sel_hi:[0,1,1]
	v_pk_fma_f32 v[54:55], v[38:39], v[44:45], v[54:55] op_sel_hi:[0,1,1]
	v_mul_f32_e32 v16, 0xbfb8aa3b, v54
	v_exp_f32_e32 v16, v16
	s_nop 0
	v_add_f32_e32 v16, 1.0, v16
	v_rcp_f32_e32 v70, v16
	v_mul_f32_e32 v16, 0xbfb8aa3b, v55
	v_exp_f32_e32 v16, v16
	s_nop 0
	v_add_f32_e32 v16, 1.0, v16
	v_rcp_f32_e32 v71, v16
	s_nop 0
	v_pk_mul_f32 v[54:55], v[54:55], v[70:71]
	v_pk_mul_f32 v[70:71], v[48:49], v[50:51]
	v_pk_mul_f32 v[50:51], v[54:55], v[54:55]
	ds_bpermute_b32 v50, v161, v50
	ds_bpermute_b32 v51, v161, v51
	s_waitcnt lgkmcnt(0)
	v_pk_fma_f32 v[50:51], v[54:55], v[54:55], v[50:51]
	ds_bpermute_b32 v74, v160, v50
	ds_bpermute_b32 v75, v160, v51
	s_waitcnt lgkmcnt(0)
	v_pk_add_f32 v[50:51], v[50:51], v[74:75]
	ds_bpermute_b32 v74, v159, v50
	ds_bpermute_b32 v75, v159, v51
	s_waitcnt lgkmcnt(0)
	v_pk_add_f32 v[50:51], v[50:51], v[74:75]
	ds_bpermute_b32 v74, v158, v50
	ds_bpermute_b32 v75, v158, v51
	s_waitcnt lgkmcnt(0)
	v_pk_add_f32 v[50:51], v[50:51], v[74:75]
	ds_bpermute_b32 v74, v29, v50
	ds_bpermute_b32 v75, v29, v51
	s_waitcnt lgkmcnt(0)
	v_pk_add_f32 v[50:51], v[50:51], v[74:75]
	v_mov_b32_e32 v74, v45
	v_pk_fma_f32 v[44:45], v[68:69], v[44:45], v[70:71] op_sel_hi:[1,0,1]
	v_mov_b32_e32 v75, v41
	v_pk_fma_f32 v[44:45], v[36:37], v[64:65], v[44:45] op_sel_hi:[0,1,1]
	v_pk_fma_f32 v[44:45], v[38:39], v[40:41], v[44:45] op_sel_hi:[0,1,1]
	v_mul_f32_e32 v16, 0xbfb8aa3b, v44
	v_exp_f32_e32 v16, v16
	v_pk_mul_f32 v[74:75], v[48:49], v[74:75]
	v_add_f32_e32 v16, 1.0, v16
	v_rcp_f32_e32 v64, v16
	v_mul_f32_e32 v16, 0xbfb8aa3b, v45
	v_exp_f32_e32 v16, v16
	s_nop 0
	v_add_f32_e32 v16, 1.0, v16
	v_rcp_f32_e32 v65, v16
	s_nop 0
	v_pk_mul_f32 v[44:45], v[44:45], v[64:65]
	s_nop 0
	v_pk_mul_f32 v[64:65], v[44:45], v[44:45]
	ds_bpermute_b32 v64, v161, v64
	ds_bpermute_b32 v65, v161, v65
	s_waitcnt lgkmcnt(0)
	v_pk_fma_f32 v[64:65], v[44:45], v[44:45], v[64:65]
	ds_bpermute_b32 v70, v160, v64
	ds_bpermute_b32 v71, v160, v65
	s_waitcnt lgkmcnt(0)
	v_pk_add_f32 v[64:65], v[64:65], v[70:71]
	ds_bpermute_b32 v70, v159, v64
	ds_bpermute_b32 v71, v159, v65
	s_waitcnt lgkmcnt(0)
	v_pk_add_f32 v[64:65], v[64:65], v[70:71]
	ds_bpermute_b32 v70, v158, v64
	ds_bpermute_b32 v71, v158, v65
	s_waitcnt lgkmcnt(0)
	v_pk_add_f32 v[64:65], v[64:65], v[70:71]
	ds_bpermute_b32 v70, v29, v64
	ds_bpermute_b32 v71, v29, v65
	s_waitcnt lgkmcnt(0)
	v_pk_add_f32 v[64:65], v[64:65], v[70:71]
	v_mov_b32_e32 v70, v41
	v_mov_b32_e32 v71, v5
	v_pk_mul_f32 v[70:71], v[48:49], v[70:71]
	v_pk_mov_b32 v[48:49], v[40:41], v[4:5] op_sel:[1,0]
	v_pk_fma_f32 v[40:41], v[68:69], v[40:41], v[74:75] op_sel_hi:[1,0,1]
	s_nop 0
	v_pk_fma_f32 v[40:41], v[36:37], v[48:49], v[40:41] op_sel_hi:[0,1,1]
	v_pk_fma_f32 v[40:41], v[38:39], v[4:5], v[40:41] op_sel_hi:[0,1,1]
	v_mul_f32_e32 v16, 0xbfb8aa3b, v41
	v_exp_f32_e32 v16, v16
	s_nop 0
	v_add_f32_e32 v16, 1.0, v16
	v_rcp_f32_e32 v49, v16
	v_mul_f32_e32 v16, 0xbfb8aa3b, v40
	v_exp_f32_e32 v16, v16
	s_nop 0
	v_add_f32_e32 v16, 1.0, v16
	v_rcp_f32_e32 v48, v16
	s_nop 0
	v_pk_mul_f32 v[40:41], v[40:41], v[48:49]
	s_nop 0
	v_pk_mul_f32 v[48:49], v[40:41], v[40:41]
	ds_bpermute_b32 v49, v161, v49
	ds_bpermute_b32 v48, v161, v48
	s_waitcnt lgkmcnt(0)
	v_pk_fma_f32 v[48:49], v[40:41], v[40:41], v[48:49]
	ds_bpermute_b32 v75, v160, v49
	ds_bpermute_b32 v74, v160, v48
	s_waitcnt lgkmcnt(0)
	v_pk_add_f32 v[48:49], v[48:49], v[74:75]
	ds_bpermute_b32 v75, v159, v49
	ds_bpermute_b32 v74, v159, v48
	s_waitcnt lgkmcnt(0)
	v_pk_add_f32 v[48:49], v[48:49], v[74:75]
	ds_bpermute_b32 v75, v158, v49
	ds_bpermute_b32 v74, v158, v48
	s_waitcnt lgkmcnt(0)
	v_pk_add_f32 v[48:49], v[48:49], v[74:75]
	ds_bpermute_b32 v74, v29, v48
	ds_bpermute_b32 v75, v29, v49
	s_waitcnt lgkmcnt(0)
	v_pk_add_f32 v[48:49], v[48:49], v[74:75]
	v_pk_mov_b32 v[74:75], v[0:1], v[2:3] op_sel:[1,0]
	v_pk_fma_f32 v[0:1], v[62:63], v[0:1], v[66:67] op_sel_hi:[1,0,1]
	s_nop 0
	v_pk_fma_f32 v[0:1], v[32:33], v[74:75], v[0:1] op_sel_hi:[0,1,1]
	v_pk_fma_f32 v[0:1], v[34:35], v[2:3], v[0:1] op_sel_hi:[0,1,1]
	v_mul_f32_e32 v2, 0xbfb8aa3b, v1
	v_exp_f32_e32 v2, v2
	s_nop 0
	v_add_f32_e32 v2, 1.0, v2
	v_rcp_f32_e32 v3, v2
	v_mul_f32_e32 v2, 0xbfb8aa3b, v0
	v_exp_f32_e32 v2, v2
	s_nop 0
	v_add_f32_e32 v2, 1.0, v2
	v_rcp_f32_e32 v2, v2
	s_nop 0
	v_pk_mul_f32 v[32:33], v[0:1], v[2:3]
	s_nop 0
	v_pk_mul_f32 v[0:1], v[32:33], v[32:33]
	ds_bpermute_b32 v1, v161, v1
	ds_bpermute_b32 v0, v161, v0
	s_waitcnt lgkmcnt(0)
	v_pk_fma_f32 v[0:1], v[32:33], v[32:33], v[0:1]
	ds_bpermute_b32 v3, v160, v1
	ds_bpermute_b32 v2, v160, v0
	s_waitcnt lgkmcnt(0)
	v_pk_add_f32 v[0:1], v[0:1], v[2:3]
	ds_bpermute_b32 v3, v159, v1
	ds_bpermute_b32 v2, v159, v0
	s_waitcnt lgkmcnt(0)
	v_pk_add_f32 v[0:1], v[0:1], v[2:3]
	ds_bpermute_b32 v3, v158, v1
	ds_bpermute_b32 v2, v158, v0
	s_waitcnt lgkmcnt(0)
	v_pk_add_f32 v[0:1], v[0:1], v[2:3]
	ds_bpermute_b32 v2, v29, v0
	ds_bpermute_b32 v3, v29, v1
	s_waitcnt lgkmcnt(0)
	v_pk_add_f32 v[0:1], v[0:1], v[2:3]
	v_pk_mov_b32 v[2:3], v[4:5], v[6:7] op_sel:[1,0]
	v_pk_fma_f32 v[4:5], v[68:69], v[4:5], v[70:71] op_sel_hi:[1,0,1]
	s_nop 0
	v_pk_fma_f32 v[2:3], v[36:37], v[2:3], v[4:5] op_sel_hi:[0,1,1]
	v_pk_fma_f32 v[2:3], v[38:39], v[6:7], v[2:3] op_sel_hi:[0,1,1]
	v_mul_f32_e32 v4, 0xbfb8aa3b, v3
	v_exp_f32_e32 v4, v4
	s_nop 0
	v_add_f32_e32 v4, 1.0, v4
	v_rcp_f32_e32 v5, v4
	v_mul_f32_e32 v4, 0xbfb8aa3b, v2
	v_exp_f32_e32 v4, v4
	s_nop 0
	v_add_f32_e32 v4, 1.0, v4
	v_rcp_f32_e32 v4, v4
	s_nop 0
	v_pk_mul_f32 v[34:35], v[2:3], v[4:5]
	s_nop 0
	v_pk_mul_f32 v[2:3], v[34:35], v[34:35]
	ds_bpermute_b32 v3, v161, v3
	ds_bpermute_b32 v2, v161, v2
	s_waitcnt lgkmcnt(0)
	v_pk_fma_f32 v[2:3], v[34:35], v[34:35], v[2:3]
	ds_bpermute_b32 v5, v160, v3
	ds_bpermute_b32 v4, v160, v2
	s_waitcnt lgkmcnt(0)
	v_pk_add_f32 v[2:3], v[2:3], v[4:5]
	ds_bpermute_b32 v5, v159, v3
	ds_bpermute_b32 v4, v159, v2
	s_waitcnt lgkmcnt(0)
	v_pk_add_f32 v[2:3], v[2:3], v[4:5]
	ds_bpermute_b32 v5, v158, v3
	ds_bpermute_b32 v4, v158, v2
	s_waitcnt lgkmcnt(0)
	v_pk_add_f32 v[2:3], v[2:3], v[4:5]
	ds_bpermute_b32 v4, v29, v2
	ds_bpermute_b32 v5, v29, v3
	s_waitcnt lgkmcnt(0)
	v_pk_add_f32 v[2:3], v[2:3], v[4:5]
	v_xor_b32_e32 v4, 1, v187
	v_cmp_lt_i32_e32 vcc, v4, v15
	s_nop 1
	v_cndmask_b32_e32 v4, v187, v4, vcc
	v_lshlrev_b32_e32 v163, 2, v4
	ds_bpermute_b32 v66, v163, v58
	ds_bpermute_b32 v68, v163, v50
	ds_bpermute_b32 v67, v163, v59
	ds_bpermute_b32 v69, v163, v51
	ds_bpermute_b32 v70, v163, v60
	ds_bpermute_b32 v62, v163, v64
	ds_bpermute_b32 v71, v163, v61
	ds_bpermute_b32 v63, v163, v65
	ds_bpermute_b32 v6, v163, v56
	ds_bpermute_b32 v36, v163, v48
	ds_bpermute_b32 v7, v163, v57
	ds_bpermute_b32 v37, v163, v49
	ds_bpermute_b32 v38, v163, v0
	ds_bpermute_b32 v4, v163, v2
	ds_bpermute_b32 v39, v163, v1
	ds_bpermute_b32 v5, v163, v3
	s_and_saveexec_b64 s[6:7], s[4:5]
	s_cbranch_execz .LBB0_610
	s_waitcnt lgkmcnt(13)
	v_pk_add_f32 v[58:59], v[58:59], v[66:67]
	s_waitcnt lgkmcnt(9)
	v_pk_add_f32 v[60:61], v[60:61], v[70:71]
	v_pk_add_f32 v[66:67], v[50:51], v[68:69]
	ds_write_b128 v162, v[58:61] offset:20480
	s_waitcnt lgkmcnt(9)
	v_pk_add_f32 v[68:69], v[64:65], v[62:63]
	s_waitcnt lgkmcnt(6)
	v_pk_add_f32 v[56:57], v[56:57], v[6:7]
	s_waitcnt lgkmcnt(5)
	v_pk_add_f32 v[36:37], v[48:49], v[36:37]
	s_waitcnt lgkmcnt(2)
	v_pk_add_f32 v[58:59], v[0:1], v[38:39]
	s_waitcnt lgkmcnt(1)
	v_pk_add_f32 v[38:39], v[2:3], v[4:5]
	ds_write_b128 v162, v[66:69] offset:20512
	ds_write_b128 v162, v[56:59] offset:20496
	ds_write_b128 v162, v[36:39] offset:20528
.LBB0_610:
	s_or_b64 exec, exec, s[6:7]
	v_ashrrev_i32_e32 v27, 31, v26
	v_cmp_gt_u32_e32 vcc, 8, v72
	s_and_saveexec_b64 s[6:7], vcc
	s_cbranch_execz .LBB0_614
	v_or_b32_e32 v0, v26, v72
	v_ashrrev_i32_e32 v1, 31, v0
	v_lshlrev_b64 v[0:1], 7, v[0:1]
	v_lshlrev_b32_e32 v16, 2, v9
	v_lshl_add_u64 v[0:1], s[80:81], 0, v[0:1]
	v_lshl_add_u64 v[0:1], v[0:1], 0, v[16:17]
	v_mov_b32_e32 v3, v104
	s_waitcnt lgkmcnt(2)
	v_mov_b32_e32 v4, v105
	v_mov_b32_e32 v2, v106
	s_mov_b32 s8, 0x41a00000
	s_waitcnt vmcnt(1)
	v_add_f32_e32 v3, v3, v4
	v_cmp_nlt_f32_e32 vcc, s8, v3
	s_and_saveexec_b64 s[8:9], vcc
	s_cbranch_execz .LBB0_613
	v_mul_f32_e32 v3, 0x3fb8aa3b, v3
	v_exp_f32_e32 v3, v3
	s_mov_b32 s33, 0x3f2aaaab
	v_add_f32_e32 v6, 1.0, v3
	v_frexp_mant_f32_e32 v9, v6
	s_waitcnt lgkmcnt(0)
	v_cvt_f64_f32_e32 v[4:5], v6
	v_frexp_exp_i32_f64_e32 v4, v[4:5]
	v_cmp_gt_f32_e32 vcc, s33, v9
	v_add_f32_e32 v7, -1.0, v6
	v_sub_f32_e32 v11, v7, v6
	v_subbrev_co_u32_e32 v9, vcc, 0, v4, vcc
	v_sub_u32_e32 v4, 0, v9
	v_sub_f32_e32 v7, v3, v7
	v_add_f32_e32 v11, 1.0, v11
	v_ldexp_f32 v5, v6, v4
	v_add_f32_e32 v7, v7, v11
	v_add_f32_e32 v6, -1.0, v5
	v_add_f32_e32 v11, 1.0, v5
	v_ldexp_f32 v4, v7, v4
	v_add_f32_e32 v7, 1.0, v6
	v_add_f32_e32 v13, -1.0, v11
	v_sub_f32_e32 v7, v5, v7
	v_sub_f32_e32 v5, v5, v13
	v_add_f32_e32 v7, v4, v7
	v_add_f32_e32 v4, v4, v5
	v_add_f32_e32 v13, v11, v4
	v_rcp_f32_e32 v15, v13
	v_sub_f32_e32 v5, v13, v11
	v_sub_f32_e32 v11, v4, v5
	v_add_f32_e32 v5, v6, v7
	v_mul_f32_e32 v19, v5, v15
	v_sub_f32_e32 v4, v5, v6
	v_mul_f32_e32 v6, v13, v19
	v_fma_f32 v36, v19, v13, -v6
	v_fmac_f32_e32 v36, v19, v11
	v_sub_f32_e32 v16, v7, v4
	v_add_f32_e32 v4, v6, v36
	v_sub_f32_e32 v7, v5, v4
	v_pk_add_f32 v[38:39], v[4:5], v[6:7] neg_lo:[0,1] neg_hi:[0,1]
	v_mov_b32_e32 v37, v4
	v_pk_add_f32 v[4:5], v[38:39], v[36:37] neg_lo:[0,1] neg_hi:[0,1]
	s_mov_b32 s33, 0x3f317218
	v_add_f32_e32 v5, v16, v5
	v_add_f32_e32 v4, v4, v5
	v_add_f32_e32 v5, v7, v4
	v_mul_f32_e32 v16, v15, v5
	v_mul_f32_e32 v6, v13, v16
	v_fma_f32 v36, v16, v13, -v6
	v_fmac_f32_e32 v36, v16, v11
	v_sub_f32_e32 v7, v7, v5
	v_add_f32_e32 v11, v4, v7
	v_add_f32_e32 v4, v6, v36
	v_sub_f32_e32 v7, v5, v4
	v_pk_add_f32 v[38:39], v[4:5], v[6:7] neg_lo:[0,1] neg_hi:[0,1]
	v_mov_b32_e32 v37, v4
	v_pk_add_f32 v[4:5], v[38:39], v[36:37] neg_lo:[0,1] neg_hi:[0,1]
	s_nop 0
	v_add_f32_e32 v5, v11, v5
	v_add_f32_e32 v4, v4, v5
	v_add_f32_e32 v5, v19, v16
	v_add_f32_e32 v4, v7, v4
	v_sub_f32_e32 v6, v5, v19
	v_mul_f32_e32 v4, v15, v4
	v_sub_f32_e32 v6, v16, v6
	v_add_f32_e32 v6, v6, v4
	v_add_f32_e32 v11, v5, v6
	v_mul_f32_e32 v13, v11, v11
	v_fmamk_f32 v4, v13, 0x3e9b6dac, v177
	v_fmaak_f32 v19, v13, v4, 0x3f2aaada
	v_cvt_f32_i32_e32 v4, v9
	v_sub_f32_e32 v5, v11, v5
	v_sub_f32_e32 v5, v6, v5
	v_ldexp_f32 v9, v5, 1
	v_mul_f32_e32 v5, v11, v13
	v_pk_mul_f32 v[36:37], v[4:5], v[18:19]
	v_ldexp_f32 v7, v11, 1
	v_fma_f32 v6, v4, s33, -v36
	v_fmac_f32_e32 v6, 0xb102e308, v4
	v_pk_add_f32 v[4:5], v[36:37], v[6:7]
	v_mov_b32_e32 v38, v36
	v_sub_f32_e32 v7, v5, v7
	v_sub_f32_e32 v7, v37, v7
	v_add_f32_e32 v39, v9, v7
	v_pk_add_f32 v[36:37], v[4:5], v[36:37] neg_lo:[0,1] neg_hi:[0,1]
	v_pk_add_f32 v[48:49], v[4:5], v[38:39]
	v_mov_b32_e32 v7, v4
	v_mov_b32_e32 v37, v49
	v_pk_add_f32 v[50:51], v[6:7], v[36:37] neg_lo:[0,1] neg_hi:[0,1]
	v_pk_add_f32 v[6:7], v[6:7], v[36:37]
	v_mov_b32_e32 v38, v39
	v_pk_add_f32 v[36:37], v[6:7], v[4:5] op_sel:[1,0] op_sel_hi:[0,1] neg_lo:[0,1] neg_hi:[0,1]
	v_pk_add_f32 v[56:57], v[48:49], v[36:37] op_sel_hi:[1,0] neg_lo:[0,1] neg_hi:[0,1]
	v_mov_b32_e32 v48, v49
	v_mov_b32_e32 v49, v7
	v_pk_mov_b32 v[36:37], v[4:5], v[36:37] op_sel:[1,0]
	v_mov_b32_e32 v39, v4
	v_pk_add_f32 v[36:37], v[48:49], v[36:37] neg_lo:[0,1] neg_hi:[0,1]
	v_mov_b32_e32 v56, v50
	v_pk_add_f32 v[4:5], v[38:39], v[36:37] neg_lo:[0,1] neg_hi:[0,1]
	v_mov_b32_e32 v51, v7
	v_pk_add_f32 v[36:37], v[56:57], v[4:5]
	s_mov_b32 s33, 0x7f800000
	v_pk_add_f32 v[38:39], v[36:37], v[36:37] op_sel:[0,1] op_sel_hi:[1,0]
	v_cmp_neq_f32_e32 vcc, s33, v3
	v_pk_add_f32 v[6:7], v[6:7], v[38:39] op_sel:[1,0] op_sel_hi:[0,1]
	v_mov_b32_e32 v37, v6
	v_pk_add_f32 v[48:49], v[36:37], v[50:51] neg_lo:[0,1] neg_hi:[0,1]
	v_mov_b32_e32 v5, v38
	v_sub_f32_e32 v7, v36, v48
	v_pk_add_f32 v[4:5], v[4:5], v[48:49] neg_lo:[0,1] neg_hi:[0,1]
	v_sub_f32_e32 v7, v50, v7
	v_add_f32_e32 v4, v4, v7
	v_add_f32_e32 v4, v4, v5
	v_add_f32_e32 v4, v6, v4
	v_cndmask_b32_e32 v4, v184, v4, vcc
	v_cmp_ngt_f32_e32 vcc, -1.0, v3
	s_mov_b32 s33, 0x33800000
	s_nop 0
	v_cndmask_b32_e32 v4, v185, v4, vcc
	v_cmp_neq_f32_e32 vcc, -1.0, v3
	s_nop 1
	v_cndmask_b32_e32 v4, v186, v4, vcc
	v_cmp_lt_f32_e64 vcc, |v3|, s33
	s_nop 1
	v_cndmask_b32_e32 v3, v4, v3, vcc
.LBB0_613:
	s_or_b64 exec, exec, s[8:9]
	v_mov_b32_e32 v0, v107
	s_waitcnt vmcnt(1)
	v_mul_f32_e32 v1, 0x3fb8aa3b, v2
	v_exp_f32_e32 v1, v1
	s_waitcnt vmcnt(0)
	v_mul_f32_e32 v0, 0xbfb8aa3b, v0
	v_exp_f32_e32 v2, v0
	v_mul_f32_e32 v0, v3, v1
	v_mul_f32_e32 v0, 0xbfb8aa3b, v0
	v_exp_f32_e32 v0, v0
	v_add_f32_e32 v1, 1.0, v2
	v_rcp_f32_e32 v1, v1
	v_lshl_add_u32 v2, v72, 3, v156
	ds_write_b64 v2, v[0:1] offset:20608
